# decode role second half-page: exponentials and row sum first, then value MFMAs with V fragments read four ahead
# speedup vs baseline: 1.0258x; 1.0016x over previous
.LBB0_942:
	v_lshlrev_b32_e32 v237, 6, v238
	v_add_u32_e32 v238, v234, v237
	v_add_u32_e32 v244, v235, v237
	ds_read_b64_tr_b16 v[240:241], v238
	ds_read_b64_tr_b16 v[242:243], v244
	v_xor_b32_e32 v250, 64, v237
	v_add_u32_e32 v245, v234, v250
	v_add_u32_e32 v246, v235, v250
	v_xor_b32_e32 v250, 0x80, v237
	v_add_u32_e32 v247, v234, v250
	v_add_u32_e32 v248, v235, v250
	v_xor_b32_e32 v250, 0xc0, v237
	v_add_u32_e32 v249, v234, v250
	v_add_u32_e32 v237, v235, v250
	v_sub_f32_e32 v68, v68, v236
	v_sub_f32_e32 v69, v69, v236
	v_sub_f32_e32 v70, v70, v236
	v_sub_f32_e32 v71, v71, v236
	v_sub_f32_e32 v72, v72, v236
	v_sub_f32_e32 v73, v73, v236
	v_sub_f32_e32 v74, v74, v236
	v_sub_f32_e32 v75, v75, v236
	v_sub_f32_e32 v76, v76, v236
	v_sub_f32_e32 v77, v77, v236
	v_sub_f32_e32 v78, v78, v236
	v_sub_f32_e32 v79, v79, v236
	v_sub_f32_e32 v80, v80, v236
	v_sub_f32_e32 v81, v81, v236
	v_sub_f32_e32 v82, v82, v236
	v_sub_f32_e32 v83, v83, v236
	v_exp_f32_e32 v68, v68
	v_exp_f32_e32 v69, v69
	v_exp_f32_e32 v70, v70
	v_exp_f32_e32 v71, v71
	v_exp_f32_e32 v72, v72
	v_exp_f32_e32 v73, v73
	v_exp_f32_e32 v74, v74
	v_exp_f32_e32 v75, v75
	v_exp_f32_e32 v76, v76
	v_exp_f32_e32 v77, v77
	v_exp_f32_e32 v78, v78
	v_exp_f32_e32 v79, v79
	v_exp_f32_e32 v80, v80
	v_exp_f32_e32 v81, v81
	v_exp_f32_e32 v82, v82
	v_exp_f32_e32 v83, v83
	v_add_f32_e32 v250, 0, v68
	v_add_f32_e32 v251, 0, v69
	v_add_f32_e32 v250, v70, v250
	v_add_f32_e32 v251, v71, v251
	v_add_f32_e32 v250, v72, v250
	v_add_f32_e32 v251, v73, v251
	v_add_f32_e32 v250, v74, v250
	v_add_f32_e32 v251, v75, v251
	v_add_f32_e32 v250, v76, v250
	v_add_f32_e32 v251, v77, v251
	v_add_f32_e32 v250, v78, v250
	v_add_f32_e32 v251, v79, v251
	v_add_f32_e32 v250, v80, v250
	v_add_f32_e32 v251, v81, v251
	v_add_f32_e32 v250, v82, v250
	v_add_f32_e32 v251, v83, v251
	v_add_f32_e32 v250, v250, v251
	v_add_f32_e32 v3, v3, v250
	v_cvt_pk_bf16_f32 v210, v68, v69
	v_cvt_pk_bf16_f32 v211, v70, v71
	v_cvt_pk_bf16_f32 v212, v72, v73
	v_cvt_pk_bf16_f32 v213, v74, v75
	v_cvt_pk_bf16_f32 v76, v76, v77
	v_cvt_pk_bf16_f32 v77, v78, v79
	v_cvt_pk_bf16_f32 v78, v80, v81
	v_cvt_pk_bf16_f32 v79, v82, v83
	ds_read_b64_tr_b16 v[68:69], v245
	ds_read_b64_tr_b16 v[70:71], v246
	ds_read_b64_tr_b16 v[72:73], v247
	ds_read_b64_tr_b16 v[74:75], v248
	ds_read_b64_tr_b16 v[80:81], v249
	ds_read_b64_tr_b16 v[82:83], v237
	s_cmpk_gt_u32 s16, 0x7d
	s_cselect_b64 s[8:9], -1, 0
	s_waitcnt lgkmcnt(6)
	v_mfma_f32_32x32x16_bf16 v[52:67], v[240:243], v[210:213], v[52:67]
	ds_read_b64_tr_b16 v[240:241], v238 offset:4096
	ds_read_b64_tr_b16 v[242:243], v244 offset:4096
	s_waitcnt lgkmcnt(6)
	v_mfma_f32_32x32x16_bf16 v[36:51], v[68:71], v[210:213], v[36:51]
	ds_read_b64_tr_b16 v[68:69], v245 offset:4096
	ds_read_b64_tr_b16 v[70:71], v246 offset:4096
	s_waitcnt lgkmcnt(6)
	v_mfma_f32_32x32x16_bf16 v[20:35], v[72:75], v[210:213], v[20:35]
	ds_read_b64_tr_b16 v[72:73], v247 offset:4096
	ds_read_b64_tr_b16 v[74:75], v248 offset:4096
	s_waitcnt lgkmcnt(6)
	v_mfma_f32_32x32x16_bf16 v[4:19], v[80:83], v[210:213], v[4:19]
	ds_read_b64_tr_b16 v[80:81], v249 offset:4096
	ds_read_b64_tr_b16 v[82:83], v237 offset:4096
	s_waitcnt lgkmcnt(6)
	v_mfma_f32_32x32x16_bf16 v[52:67], v[240:243], v[76:79], v[52:67]
	s_waitcnt lgkmcnt(4)
	v_mfma_f32_32x32x16_bf16 v[36:51], v[68:71], v[76:79], v[36:51]
	s_waitcnt lgkmcnt(2)
	v_mfma_f32_32x32x16_bf16 v[20:35], v[72:75], v[76:79], v[20:35]
	s_waitcnt lgkmcnt(0)
	v_mfma_f32_32x32x16_bf16 v[4:19], v[80:83], v[76:79], v[4:19]
	s_and_b64 vcc, exec, s[8:9]
	s_cbranch_vccnz .LBB0_944
	s_waitcnt vmcnt(13)
	v_cvt_pk_bf16_f32 v184, v184, v185
	v_cvt_pk_bf16_f32 v185, v186, v187
	v_cvt_pk_bf16_f32 v180, v180, v181
	v_cvt_pk_bf16_f32 v181, v182, v183
	v_cvt_pk_bf16_f32 v172, v172, v173
	v_cvt_pk_bf16_f32 v173, v174, v175
	ds_write_b64 v204, v[184:185]
	ds_write_b64 v205, v[180:181] offset:63488
	ds_write_b64 v204, v[172:173] offset:4096
	v_cvt_pk_bf16_f32 v172, v176, v177
	v_cvt_pk_bf16_f32 v173, v178, v179
	v_cvt_pk_bf16_f32 v164, v164, v165
	v_cvt_pk_bf16_f32 v165, v166, v167
	ds_write_b64 v206, v[172:173] offset:6144
	ds_write_b64 v204, v[164:165] offset:8192
	v_cvt_pk_bf16_f32 v164, v168, v169
	v_cvt_pk_bf16_f32 v165, v170, v171
	v_cvt_pk_bf16_f32 v148, v148, v149
	v_cvt_pk_bf16_f32 v149, v150, v151
	ds_write_b64 v206, v[164:165] offset:10240
	ds_write_b64 v204, v[148:149] offset:12288
	s_waitcnt vmcnt(12)
	v_cvt_pk_bf16_f32 v148, v156, v157
	v_cvt_pk_bf16_f32 v149, v158, v159
	ds_write_b64 v206, v[148:149] offset:14336
	s_waitcnt vmcnt(11)
	v_cvt_pk_bf16_f32 v148, v160, v161
	v_cvt_pk_bf16_f32 v149, v162, v163
	s_waitcnt vmcnt(10)
	v_cvt_pk_bf16_f32 v150, v152, v153
	v_cvt_pk_bf16_f32 v151, v154, v155
	ds_write2st64_b64 v221, v[148:149], v[150:151] offset1:4

.LBB0_949:
	s_and_b64 vcc, exec, s[8:9]
	s_cbranch_vccnz .LBB0_951
	s_mov_b32 s16, s33
	s_branch .LBB0_930
